# mlstm_s: redundant third workgroup barrier per item removed
# baseline (speedup 1.0000x reference)
; #define LAS __attribute__((address_space(3)))
; __device__ __forceinline__ bf16_t f2bf(float f) { unsigned u = __float_as_uint(f); u += 0x7FFFu + ((u >> 16) & 1u); return (bf16_t)(u >> 16); }
; __device__ __forceinline__ void phase_mlstm_s(const Ctx& c, int p, int l) {
;     ...
;             for (int r = 0; r < 4; ++r) {
;                 const int t = 16 * ti + (lane >> 4) * 4 + r, s2 = 16 * sj + (lane & 15);
;                 const float wg = (s2 <= t && t < nvalid) ? __expf(bcum[t] - bcum[s2] + igs[s2] - mloc[t]) : 0.f;
;                 St[t * 72 + s2] = f2bf(a[r] * wg);
;             }
;         }
;         __syncthreads();
;         { const int row = tid >> 3, pc = tid & 7; *(u32x4*)(SL + (size_t)item * 4096 + row * 64 + 8 * pc) = *(const LAS u32x4*)(St + row * 72 + 8 * pc); }
;         __syncthreads();
;     }
.LBB0_1081:
	s_or_b64 exec, exec, s[2:3]
	v_mul_f32_e32 v1, v3, v1
	v_bfe_u32 v2, v1, 16, 1
	v_add3_u32 v1, v1, v2, s1
	ds_write_b16_d16_hi v0, v1 offset:432
	v_ashrrev_i32_e32 v4, 3, v12
	v_and_b32_e32 v1, 56, v14
	v_mul_lo_u32 v0, v4, s81
	v_lshlrev_b32_e32 v1, 1, v1
	v_lshlrev_b32_e32 v4, 6, v4
	v_add3_u32 v0, v10, v0, v1
	v_ashrrev_i32_e32 v5, 31, v4
	s_waitcnt lgkmcnt(0)
	s_barrier
	ds_read_b128 v[0:3], v0
	v_and_b32_e32 v6, 7, v12
	v_lshlrev_b64 v[4:5], 1, v[4:5]
	v_readlane_b32 s2, v254, 40
	v_lshl_or_b32 v4, v6, 4, v4
	s_add_i32 s37, s37, s2
	s_add_i32 s29, s29, s30
	s_add_i32 s31, s31, s34
	s_add_i32 s35, s35, s36
	v_lshl_add_u64 v[4:5], s[20:21], 0, v[4:5]
	s_add_u32 s20, s20, s22
	s_addc_u32 s21, s21, s23
	s_cmp_lt_i32 s37, s0
	s_waitcnt lgkmcnt(0)
	global_store_dwordx4 v[4:5], v[0:3], off
	v_readlane_b32 s3, v254, 41
	s_cbranch_scc0 .LBB0_1114
